# MMA-block priority raised to 3 in all four GEMM K-loops (was 1)
# baseline (speedup 1.0000x reference)
.LBB0_222:
	s_add_u32 s6, s0, 0xfffc0080
	s_addc_u32 s7, s1, -1
	s_add_i32 s39, 0, 0x10000
	s_cmp_eq_u32 s38, 12
	s_cselect_b32 s7, s8, s7
	s_cselect_b32 s6, s9, s6
	v_add_u32_e32 v0, s39, v173
	s_cselect_b32 s45, s27, s37
	s_cselect_b32 s44, s29, s36
	s_add_i32 s41, 0, 0x14000
	ds_read_b128 v[22:25], v0
	ds_read_b128 v[26:29], v0 offset:1024
	ds_read_b128 v[34:37], v0 offset:2048
	ds_read_b128 v[38:41], v0 offset:3072
	v_add_u32_e32 v0, s41, v173
	ds_read_b128 v[146:149], v0
	ds_read_b128 v[150:153], v0 offset:1024
	ds_read_b128 v[154:157], v0 offset:2048
	ds_read_b128 v[158:161], v0 offset:3072
	v_lshl_add_u64 v[218:219], s[0:1], 0, v[202:203]
	s_add_i32 m0, s2, 0xc000
	ds_read_b128 v[204:207], v209
	ds_read_b128 v[214:217], v209 offset:1024
	ds_read_b128 v[228:231], v209 offset:2048
	ds_read_b128 v[232:235], v209 offset:3072
	ds_read_b128 v[236:239], v209 offset:4096
	ds_read_b128 v[240:243], v209 offset:5120
	ds_read_b128 v[244:247], v209 offset:6144
	ds_read_b128 v[248:251], v209 offset:7168
	global_load_lds_dwordx4 v[218:219], off
	v_lshl_add_u64 v[218:219], v[218:219], 0, s[94:95]
	s_add_i32 m0, s2, 0xe000
	s_nop 0
	global_load_lds_dwordx4 v[218:219], off
	s_waitcnt vmcnt(8)
	s_waitcnt lgkmcnt(0)
	s_barrier
	s_setprio 3
	v_mfma_f32_16x16x32_bf16 v[162:165], v[22:25], v[204:207], v[162:165]
	v_mfma_f32_16x16x32_bf16 v[142:145], v[34:37], v[204:207], v[142:145]
	v_mfma_f32_16x16x32_bf16 v[130:133], v[22:25], v[228:231], v[130:133]
	v_mfma_f32_16x16x32_bf16 v[126:129], v[34:37], v[228:231], v[126:129]
	v_mfma_f32_16x16x32_bf16 v[114:117], v[22:25], v[236:239], v[114:117]
	v_mfma_f32_16x16x32_bf16 v[110:113], v[34:37], v[236:239], v[110:113]
	v_mfma_f32_16x16x32_bf16 v[98:101], v[22:25], v[244:247], v[98:101]
	v_mfma_f32_16x16x32_bf16 v[94:97], v[34:37], v[244:247], v[94:97]
	v_mfma_f32_16x16x32_bf16 v[162:165], v[26:29], v[214:217], v[162:165]
	v_mfma_f32_16x16x32_bf16 v[142:145], v[38:41], v[214:217], v[142:145]
	v_mfma_f32_16x16x32_bf16 v[130:133], v[26:29], v[232:235], v[130:133]
	v_mfma_f32_16x16x32_bf16 v[126:129], v[38:41], v[232:235], v[126:129]
	v_mfma_f32_16x16x32_bf16 v[114:117], v[26:29], v[240:243], v[114:117]
	v_mfma_f32_16x16x32_bf16 v[110:113], v[38:41], v[240:243], v[110:113]
	v_mfma_f32_16x16x32_bf16 v[98:101], v[26:29], v[248:251], v[98:101]
	v_mfma_f32_16x16x32_bf16 v[94:97], v[38:41], v[248:251], v[94:97]
	v_mfma_f32_16x16x32_bf16 v[138:141], v[146:149], v[204:207], v[138:141]
	v_mfma_f32_16x16x32_bf16 v[134:137], v[154:157], v[204:207], v[134:137]
	v_mfma_f32_16x16x32_bf16 v[122:125], v[146:149], v[228:231], v[122:125]
	v_mfma_f32_16x16x32_bf16 v[118:121], v[154:157], v[228:231], v[118:121]
	v_mfma_f32_16x16x32_bf16 v[106:109], v[146:149], v[236:239], v[106:109]
	v_mfma_f32_16x16x32_bf16 v[102:105], v[154:157], v[236:239], v[102:105]
	v_mfma_f32_16x16x32_bf16 v[90:93], v[146:149], v[244:247], v[90:93]
	v_mfma_f32_16x16x32_bf16 v[86:89], v[154:157], v[244:247], v[86:89]
	v_mfma_f32_16x16x32_bf16 v[138:141], v[150:153], v[214:217], v[138:141]
	v_mfma_f32_16x16x32_bf16 v[134:137], v[158:161], v[214:217], v[134:137]
	v_mfma_f32_16x16x32_bf16 v[122:125], v[150:153], v[232:235], v[122:125]
	v_mfma_f32_16x16x32_bf16 v[118:121], v[158:161], v[232:235], v[118:121]
	v_mfma_f32_16x16x32_bf16 v[106:109], v[150:153], v[240:243], v[106:109]
	v_mfma_f32_16x16x32_bf16 v[102:105], v[158:161], v[240:243], v[102:105]
	v_mfma_f32_16x16x32_bf16 v[90:93], v[150:153], v[248:251], v[90:93]
	v_mfma_f32_16x16x32_bf16 v[86:89], v[158:161], v[248:251], v[86:89]
	s_setprio 0
	s_barrier
	s_add_i32 s39, s39, s43
	v_lshl_add_u64 v[218:219], s[44:45], 0, v[166:167]
	s_mov_b32 m0, s39
	ds_read_b128 v[204:207], v209 offset:16384
	ds_read_b128 v[214:217], v209 offset:17408
	ds_read_b128 v[228:231], v209 offset:18432
	ds_read_b128 v[232:235], v209 offset:19456
	ds_read_b128 v[236:239], v209 offset:20480
	ds_read_b128 v[240:243], v209 offset:21504
	ds_read_b128 v[244:247], v209 offset:22528
	ds_read_b128 v[248:251], v209 offset:23552
	global_load_lds_dwordx4 v[218:219], off
	v_lshl_add_u64 v[252:253], v[218:219], 0, s[88:89]
	s_add_i32 m0, s39, 0x2000
	s_add_i32 s39, s41, s43
	global_load_lds_dwordx4 v[252:253], off
	v_lshl_add_u64 v[252:253], v[218:219], 0, s[90:91]
	s_mov_b32 m0, s39
	s_nop 0
	global_load_lds_dwordx4 v[252:253], off
	v_lshl_add_u64 v[252:253], v[218:219], 0, s[92:93]
	s_add_i32 m0, s39, 0x2000
	s_nop 0
	global_load_lds_dwordx4 v[252:253], off
	v_lshl_add_u64 v[252:253], s[6:7], 0, v[168:169]
	s_mov_b32 m0, s2
	v_lshl_add_u64 v[226:227], v[252:253], 0, s[94:95]
	global_load_lds_dwordx4 v[252:253], off
	s_mov_b32 m0, s3
	s_nop 0
	global_load_lds_dwordx4 v[226:227], off
	s_waitcnt vmcnt(8)
	s_waitcnt lgkmcnt(0)
	s_barrier
	s_setprio 3
	v_mfma_f32_16x16x32_bf16 v[82:85], v[22:25], v[204:207], v[82:85]
	v_mfma_f32_16x16x32_bf16 v[78:81], v[34:37], v[204:207], v[78:81]
	v_mfma_f32_16x16x32_bf16 v[66:69], v[22:25], v[228:231], v[66:69]
	v_mfma_f32_16x16x32_bf16 v[62:65], v[34:37], v[228:231], v[62:65]
	v_mfma_f32_16x16x32_bf16 v[50:53], v[22:25], v[236:239], v[50:53]
	v_mfma_f32_16x16x32_bf16 v[46:49], v[34:37], v[236:239], v[46:49]
	v_mfma_f32_16x16x32_bf16 v[18:21], v[22:25], v[244:247], v[18:21]
	v_mfma_f32_16x16x32_bf16 v[14:17], v[34:37], v[244:247], v[14:17]
	v_mfma_f32_16x16x32_bf16 v[82:85], v[26:29], v[214:217], v[82:85]
	v_mfma_f32_16x16x32_bf16 v[78:81], v[38:41], v[214:217], v[78:81]
	v_mfma_f32_16x16x32_bf16 v[66:69], v[26:29], v[232:235], v[66:69]
	v_mfma_f32_16x16x32_bf16 v[62:65], v[38:41], v[232:235], v[62:65]
	v_mfma_f32_16x16x32_bf16 v[50:53], v[26:29], v[240:243], v[50:53]
	v_mfma_f32_16x16x32_bf16 v[46:49], v[38:41], v[240:243], v[46:49]
	v_mfma_f32_16x16x32_bf16 v[18:21], v[26:29], v[248:251], v[18:21]
	v_mfma_f32_16x16x32_bf16 v[14:17], v[38:41], v[248:251], v[14:17]
	v_mfma_f32_16x16x32_bf16 v[42:45], v[146:149], v[236:239], v[42:45]
	v_mfma_f32_16x16x32_bf16 v[30:33], v[154:157], v[236:239], v[30:33]
	v_mfma_f32_16x16x32_bf16 v[10:13], v[146:149], v[244:247], v[10:13]
	v_mfma_f32_16x16x32_bf16 v[6:9], v[154:157], v[244:247], v[6:9]
	v_mfma_f32_16x16x32_bf16 v[22:25], v[146:149], v[204:207], v[74:77]
	v_mfma_f32_16x16x32_bf16 v[26:29], v[154:157], v[204:207], v[70:73]
	v_mfma_f32_16x16x32_bf16 v[34:37], v[146:149], v[228:231], v[58:61]
	v_mfma_f32_16x16x32_bf16 v[38:41], v[154:157], v[228:231], v[54:57]
	v_mfma_f32_16x16x32_bf16 v[42:45], v[150:153], v[240:243], v[42:45]
	v_mfma_f32_16x16x32_bf16 v[30:33], v[158:161], v[240:243], v[30:33]
	v_mfma_f32_16x16x32_bf16 v[10:13], v[150:153], v[248:251], v[10:13]
	v_mfma_f32_16x16x32_bf16 v[6:9], v[158:161], v[248:251], v[6:9]
	v_mfma_f32_16x16x32_bf16 v[22:25], v[150:153], v[214:217], v[22:25]
	v_mfma_f32_16x16x32_bf16 v[26:29], v[158:161], v[214:217], v[26:29]
	v_mfma_f32_16x16x32_bf16 v[34:37], v[150:153], v[232:235], v[34:37]
	v_mfma_f32_16x16x32_bf16 v[38:41], v[158:161], v[232:235], v[38:41]
	s_setprio 0
	s_barrier
	s_add_i32 s6, 0, 0x18000
	v_add_u32_e32 v0, s6, v173
	s_add_i32 s7, 0, 0x1c000
	ds_read_b128 v[54:57], v0
	ds_read_b128 v[58:61], v0 offset:1024
	ds_read_b128 v[70:73], v0 offset:2048
	ds_read_b128 v[74:77], v0 offset:3072
	v_add_u32_e32 v0, s7, v173
	ds_read_b128 v[146:149], v0
	ds_read_b128 v[150:153], v0 offset:1024
	ds_read_b128 v[154:157], v0 offset:2048
	ds_read_b128 v[158:161], v0 offset:3072
	s_mov_b32 m0, s33
	v_lshl_add_u64 v[226:227], v[252:253], 0, s[96:97]
	ds_read_b128 v[204:207], v209 offset:32768
	ds_read_b128 v[214:217], v209 offset:33792
	ds_read_b128 v[228:231], v209 offset:34816
	ds_read_b128 v[232:235], v209 offset:35840
	ds_read_b128 v[236:239], v209 offset:36864
	ds_read_b128 v[240:243], v209 offset:37888
	ds_read_b128 v[244:247], v209 offset:38912
	ds_read_b128 v[248:251], v209 offset:39936
	global_load_lds_dwordx4 v[226:227], off
	v_lshl_add_u64 v[226:227], v[252:253], 0, s[86:87]
	s_mov_b32 m0, s72
	s_nop 0
	global_load_lds_dwordx4 v[226:227], off
	s_waitcnt vmcnt(8)
	s_waitcnt lgkmcnt(0)
	s_barrier
	s_setprio 3
	v_mfma_f32_16x16x32_bf16 v[162:165], v[54:57], v[204:207], v[162:165]
	v_mfma_f32_16x16x32_bf16 v[142:145], v[70:73], v[204:207], v[142:145]
	v_mfma_f32_16x16x32_bf16 v[130:133], v[54:57], v[228:231], v[130:133]
	v_mfma_f32_16x16x32_bf16 v[126:129], v[70:73], v[228:231], v[126:129]
	v_mfma_f32_16x16x32_bf16 v[114:117], v[54:57], v[236:239], v[114:117]
	v_mfma_f32_16x16x32_bf16 v[110:113], v[70:73], v[236:239], v[110:113]
	v_mfma_f32_16x16x32_bf16 v[98:101], v[54:57], v[244:247], v[98:101]
	v_mfma_f32_16x16x32_bf16 v[94:97], v[70:73], v[244:247], v[94:97]
	v_mfma_f32_16x16x32_bf16 v[162:165], v[58:61], v[214:217], v[162:165]
	v_mfma_f32_16x16x32_bf16 v[142:145], v[74:77], v[214:217], v[142:145]
	v_mfma_f32_16x16x32_bf16 v[130:133], v[58:61], v[232:235], v[130:133]
	v_mfma_f32_16x16x32_bf16 v[126:129], v[74:77], v[232:235], v[126:129]
	v_mfma_f32_16x16x32_bf16 v[114:117], v[58:61], v[240:243], v[114:117]
	v_mfma_f32_16x16x32_bf16 v[110:113], v[74:77], v[240:243], v[110:113]
	v_mfma_f32_16x16x32_bf16 v[98:101], v[58:61], v[248:251], v[98:101]
	v_mfma_f32_16x16x32_bf16 v[94:97], v[74:77], v[248:251], v[94:97]
	v_mfma_f32_16x16x32_bf16 v[138:141], v[146:149], v[204:207], v[138:141]
	v_mfma_f32_16x16x32_bf16 v[134:137], v[154:157], v[204:207], v[134:137]
	v_mfma_f32_16x16x32_bf16 v[122:125], v[146:149], v[228:231], v[122:125]
	v_mfma_f32_16x16x32_bf16 v[118:121], v[154:157], v[228:231], v[118:121]
	v_mfma_f32_16x16x32_bf16 v[106:109], v[146:149], v[236:239], v[106:109]
	v_mfma_f32_16x16x32_bf16 v[102:105], v[154:157], v[236:239], v[102:105]
	v_mfma_f32_16x16x32_bf16 v[90:93], v[146:149], v[244:247], v[90:93]
	v_mfma_f32_16x16x32_bf16 v[86:89], v[154:157], v[244:247], v[86:89]
	v_mfma_f32_16x16x32_bf16 v[138:141], v[150:153], v[214:217], v[138:141]
	v_mfma_f32_16x16x32_bf16 v[134:137], v[158:161], v[214:217], v[134:137]
	v_mfma_f32_16x16x32_bf16 v[122:125], v[150:153], v[232:235], v[122:125]
	v_mfma_f32_16x16x32_bf16 v[118:121], v[158:161], v[232:235], v[118:121]
	v_mfma_f32_16x16x32_bf16 v[106:109], v[150:153], v[240:243], v[106:109]
	v_mfma_f32_16x16x32_bf16 v[102:105], v[158:161], v[240:243], v[102:105]
	v_mfma_f32_16x16x32_bf16 v[90:93], v[150:153], v[248:251], v[90:93]
	v_mfma_f32_16x16x32_bf16 v[86:89], v[158:161], v[248:251], v[86:89]
	s_setprio 0
	s_barrier
	s_add_i32 s6, s6, s43
	v_lshl_add_u64 v[226:227], v[218:219], 0, s[64:65]
	s_mov_b32 m0, s6
	ds_read_b128 v[204:207], v209 offset:49152
	ds_read_b128 v[214:217], v209 offset:50176
	ds_read_b128 v[228:231], v209 offset:51200
	ds_read_b128 v[232:235], v209 offset:52224
	ds_read_b128 v[236:239], v209 offset:53248
	ds_read_b128 v[240:243], v209 offset:54272
	ds_read_b128 v[244:247], v209 offset:55296
	ds_read_b128 v[248:251], v209 offset:56320
	global_load_lds_dwordx4 v[226:227], off
	v_lshl_add_u64 v[226:227], v[218:219], 0, s[62:63]
	s_add_i32 m0, s6, 0x2000
	s_add_i32 s6, s7, s43
	global_load_lds_dwordx4 v[226:227], off
	v_lshl_add_u64 v[226:227], v[218:219], 0, s[56:57]
	s_mov_b32 m0, s6
	v_lshl_add_u64 v[218:219], v[218:219], 0, s[58:59]
	global_load_lds_dwordx4 v[226:227], off
	s_add_i32 m0, s6, 0x2000
	s_nop 0
	global_load_lds_dwordx4 v[218:219], off
	v_lshl_add_u64 v[218:219], v[252:253], 0, s[66:67]
	s_mov_b32 m0, s22
	s_nop 0
	global_load_lds_dwordx4 v[218:219], off
	v_lshl_add_u64 v[218:219], v[252:253], 0, s[54:55]
	s_mov_b32 m0, s23
	s_nop 0
	global_load_lds_dwordx4 v[218:219], off
	s_waitcnt vmcnt(8)
	s_waitcnt lgkmcnt(0)
	s_barrier
	s_setprio 3
	v_mfma_f32_16x16x32_bf16 v[82:85], v[54:57], v[204:207], v[82:85]
	v_mfma_f32_16x16x32_bf16 v[78:81], v[70:73], v[204:207], v[78:81]
	v_mfma_f32_16x16x32_bf16 v[66:69], v[54:57], v[228:231], v[66:69]
	v_mfma_f32_16x16x32_bf16 v[62:65], v[70:73], v[228:231], v[62:65]
	v_mfma_f32_16x16x32_bf16 v[50:53], v[54:57], v[236:239], v[50:53]
	v_mfma_f32_16x16x32_bf16 v[46:49], v[70:73], v[236:239], v[46:49]
	v_mfma_f32_16x16x32_bf16 v[18:21], v[54:57], v[244:247], v[18:21]
	v_mfma_f32_16x16x32_bf16 v[14:17], v[70:73], v[244:247], v[14:17]
	v_mfma_f32_16x16x32_bf16 v[82:85], v[58:61], v[214:217], v[82:85]
	v_mfma_f32_16x16x32_bf16 v[78:81], v[74:77], v[214:217], v[78:81]
	v_mfma_f32_16x16x32_bf16 v[66:69], v[58:61], v[232:235], v[66:69]
	v_mfma_f32_16x16x32_bf16 v[62:65], v[74:77], v[232:235], v[62:65]
	v_mfma_f32_16x16x32_bf16 v[50:53], v[58:61], v[240:243], v[50:53]
	v_mfma_f32_16x16x32_bf16 v[46:49], v[74:77], v[240:243], v[46:49]
	v_mfma_f32_16x16x32_bf16 v[18:21], v[58:61], v[248:251], v[18:21]
	v_mfma_f32_16x16x32_bf16 v[14:17], v[74:77], v[248:251], v[14:17]
	v_mfma_f32_16x16x32_bf16 v[22:25], v[146:149], v[204:207], v[22:25]
	v_mfma_f32_16x16x32_bf16 v[74:77], v[150:153], v[214:217], v[22:25]
	v_mfma_f32_16x16x32_bf16 v[22:25], v[154:157], v[204:207], v[26:29]
	v_mfma_f32_16x16x32_bf16 v[70:73], v[158:161], v[214:217], v[22:25]
	v_mfma_f32_16x16x32_bf16 v[22:25], v[146:149], v[228:231], v[34:37]
	v_mfma_f32_16x16x32_bf16 v[58:61], v[150:153], v[232:235], v[22:25]
	v_mfma_f32_16x16x32_bf16 v[22:25], v[154:157], v[228:231], v[38:41]
	v_mfma_f32_16x16x32_bf16 v[54:57], v[158:161], v[232:235], v[22:25]
	v_mfma_f32_16x16x32_bf16 v[22:25], v[146:149], v[236:239], v[42:45]
	v_mfma_f32_16x16x32_bf16 v[42:45], v[150:153], v[240:243], v[22:25]
	v_mfma_f32_16x16x32_bf16 v[22:25], v[154:157], v[236:239], v[30:33]
	v_mfma_f32_16x16x32_bf16 v[10:13], v[146:149], v[244:247], v[10:13]
	v_mfma_f32_16x16x32_bf16 v[6:9], v[154:157], v[244:247], v[6:9]
	v_mfma_f32_16x16x32_bf16 v[30:33], v[158:161], v[240:243], v[22:25]
	v_mfma_f32_16x16x32_bf16 v[10:13], v[150:153], v[248:251], v[10:13]
	v_mfma_f32_16x16x32_bf16 v[6:9], v[158:161], v[248:251], v[6:9]
	s_setprio 0
	s_barrier
	s_add_i32 s38, s38, 2
	s_add_u32 s36, s36, 0x10000
	s_addc_u32 s37, s37, 0
	s_add_u32 s0, s0, 0x100
	s_addc_u32 s1, s1, 0
	s_cmp_gt_u32 s38, 13
	s_cbranch_scc0 .LBB0_222
	v_readlane_b32 s0, v255, 19
	v_readlane_b32 s1, v255, 20
	s_and_b64 vcc, exec, s[0:1]
	s_cbranch_vccz .LBB0_225
	s_barrier

.LBB0_1083:
	s_add_u32 s24, s22, 0xfffc0080
	s_addc_u32 s25, s23, -1
	s_add_i32 s46, 0, 0x10000
	s_cmp_eq_u32 s43, 12
	s_cselect_b32 s25, s13, s25
	s_cselect_b32 s24, s21, s24
	s_cselect_b32 s45, s11, s41
	s_cselect_b32 s44, s39, s40
	s_add_i32 s47, 0, 0x14000
	v_add_u32_e32 v130, s46, v194
	v_add_u32_e32 v158, s47, v194
	ds_read_b128 v[110:113], v130
	ds_read_b128 v[114:117], v130 offset:1024
	ds_read_b128 v[122:125], v130 offset:2048
	ds_read_b128 v[130:133], v130 offset:3072
	ds_read_b128 v[146:149], v158
	ds_read_b128 v[150:153], v158 offset:1024
	ds_read_b128 v[154:157], v158 offset:2048
	ds_read_b128 v[158:161], v158 offset:3072
	v_lshl_add_u64 v[218:219], s[22:23], 0, v[184:185]
	s_add_i32 m0, s26, 0xc000
	ds_read_b128 v[162:165], v196
	ds_read_b128 v[186:189], v196 offset:1024
	ds_read_b128 v[190:193], v196 offset:2048
	ds_read_b128 v[198:201], v196 offset:3072
	ds_read_b128 v[202:205], v196 offset:4096
	ds_read_b128 v[206:209], v196 offset:5120
	ds_read_b128 v[214:217], v196 offset:6144
	ds_read_b128 v[234:237], v196 offset:7168
	global_load_lds_dwordx4 v[218:219], off
	v_lshl_add_u64 v[218:219], v[218:219], 0, s[94:95]
	s_add_i32 m0, s26, 0xe000
	s_nop 0
	global_load_lds_dwordx4 v[218:219], off
	s_waitcnt vmcnt(8)
	s_waitcnt lgkmcnt(0)
	s_barrier
	s_setprio 3
	v_mfma_f32_16x16x32_bf16 v[142:145], v[110:113], v[162:165], v[142:145]
	v_mfma_f32_16x16x32_bf16 v[138:141], v[122:125], v[162:165], v[138:141]
	v_mfma_f32_16x16x32_bf16 v[118:121], v[110:113], v[190:193], v[118:121]
	v_mfma_f32_16x16x32_bf16 v[106:109], v[122:125], v[190:193], v[106:109]
	v_mfma_f32_16x16x32_bf16 v[94:97], v[110:113], v[202:205], v[94:97]
	v_mfma_f32_16x16x32_bf16 v[90:93], v[122:125], v[202:205], v[90:93]
	v_mfma_f32_16x16x32_bf16 v[78:81], v[110:113], v[214:217], v[78:81]
	v_mfma_f32_16x16x32_bf16 v[74:77], v[122:125], v[214:217], v[74:77]
	v_mfma_f32_16x16x32_bf16 v[142:145], v[114:117], v[186:189], v[142:145]
	v_mfma_f32_16x16x32_bf16 v[138:141], v[130:133], v[186:189], v[138:141]
	v_mfma_f32_16x16x32_bf16 v[118:121], v[114:117], v[198:201], v[118:121]
	v_mfma_f32_16x16x32_bf16 v[106:109], v[130:133], v[198:201], v[106:109]
	v_mfma_f32_16x16x32_bf16 v[94:97], v[114:117], v[206:209], v[94:97]
	v_mfma_f32_16x16x32_bf16 v[90:93], v[130:133], v[206:209], v[90:93]
	v_mfma_f32_16x16x32_bf16 v[78:81], v[114:117], v[234:237], v[78:81]
	v_mfma_f32_16x16x32_bf16 v[74:77], v[130:133], v[234:237], v[74:77]
	v_mfma_f32_16x16x32_bf16 v[134:137], v[146:149], v[162:165], v[134:137]
	v_mfma_f32_16x16x32_bf16 v[126:129], v[154:157], v[162:165], v[126:129]
	v_mfma_f32_16x16x32_bf16 v[102:105], v[146:149], v[190:193], v[102:105]
	v_mfma_f32_16x16x32_bf16 v[98:101], v[154:157], v[190:193], v[98:101]
	v_mfma_f32_16x16x32_bf16 v[86:89], v[146:149], v[202:205], v[86:89]
	v_mfma_f32_16x16x32_bf16 v[82:85], v[154:157], v[202:205], v[82:85]
	v_mfma_f32_16x16x32_bf16 v[70:73], v[146:149], v[214:217], v[70:73]
	v_mfma_f32_16x16x32_bf16 v[66:69], v[154:157], v[214:217], v[66:69]
	v_mfma_f32_16x16x32_bf16 v[134:137], v[150:153], v[186:189], v[134:137]
	v_mfma_f32_16x16x32_bf16 v[126:129], v[158:161], v[186:189], v[126:129]
	v_mfma_f32_16x16x32_bf16 v[102:105], v[150:153], v[198:201], v[102:105]
	v_mfma_f32_16x16x32_bf16 v[98:101], v[158:161], v[198:201], v[98:101]
	v_mfma_f32_16x16x32_bf16 v[86:89], v[150:153], v[206:209], v[86:89]
	v_mfma_f32_16x16x32_bf16 v[82:85], v[158:161], v[206:209], v[82:85]
	v_mfma_f32_16x16x32_bf16 v[70:73], v[150:153], v[234:237], v[70:73]
	v_mfma_f32_16x16x32_bf16 v[66:69], v[158:161], v[234:237], v[66:69]
	s_setprio 0
	s_barrier
	v_lshl_add_u64 v[218:219], s[44:45], 0, v[0:1]
	s_add_i32 s44, s46, s17
	s_mov_b32 m0, s44
	ds_read_b128 v[162:165], v196 offset:16384
	ds_read_b128 v[186:189], v196 offset:17408
	ds_read_b128 v[190:193], v196 offset:18432
	ds_read_b128 v[198:201], v196 offset:19456
	ds_read_b128 v[202:205], v196 offset:20480
	ds_read_b128 v[206:209], v196 offset:21504
	ds_read_b128 v[214:217], v196 offset:22528
	ds_read_b128 v[234:237], v196 offset:23552
	global_load_lds_dwordx4 v[218:219], off
	v_lshl_add_u64 v[238:239], v[218:219], 0, s[88:89]
	s_add_i32 m0, s44, 0x2000
	s_add_i32 s44, s47, s17
	global_load_lds_dwordx4 v[238:239], off
	v_lshl_add_u64 v[238:239], v[218:219], 0, s[90:91]
	s_mov_b32 m0, s44
	s_nop 0
	global_load_lds_dwordx4 v[238:239], off
	v_lshl_add_u64 v[238:239], v[218:219], 0, s[92:93]
	s_add_i32 m0, s44, 0x2000
	s_nop 0
	global_load_lds_dwordx4 v[238:239], off
	v_lshl_add_u64 v[238:239], s[24:25], 0, v[166:167]
	s_mov_b32 m0, s26
	v_lshl_add_u64 v[240:241], v[238:239], 0, s[94:95]
	global_load_lds_dwordx4 v[238:239], off
	s_mov_b32 m0, s27
	s_nop 0
	global_load_lds_dwordx4 v[240:241], off
	s_waitcnt vmcnt(8)
	s_waitcnt lgkmcnt(0)
	s_barrier
	s_setprio 3
	v_mfma_f32_16x16x32_bf16 v[62:65], v[110:113], v[162:165], v[62:65]
	v_mfma_f32_16x16x32_bf16 v[58:61], v[122:125], v[162:165], v[58:61]
	v_mfma_f32_16x16x32_bf16 v[46:49], v[110:113], v[190:193], v[46:49]
	v_mfma_f32_16x16x32_bf16 v[42:45], v[122:125], v[190:193], v[42:45]
	v_mfma_f32_16x16x32_bf16 v[30:33], v[110:113], v[202:205], v[30:33]
	v_mfma_f32_16x16x32_bf16 v[26:29], v[122:125], v[202:205], v[26:29]
	v_mfma_f32_16x16x32_bf16 v[14:17], v[110:113], v[214:217], v[14:17]
	v_mfma_f32_16x16x32_bf16 v[10:13], v[122:125], v[214:217], v[10:13]
	v_mfma_f32_16x16x32_bf16 v[62:65], v[114:117], v[186:189], v[62:65]
	v_mfma_f32_16x16x32_bf16 v[58:61], v[130:133], v[186:189], v[58:61]
	v_mfma_f32_16x16x32_bf16 v[46:49], v[114:117], v[198:201], v[46:49]
	v_mfma_f32_16x16x32_bf16 v[42:45], v[130:133], v[198:201], v[42:45]
	v_mfma_f32_16x16x32_bf16 v[30:33], v[114:117], v[206:209], v[30:33]
	v_mfma_f32_16x16x32_bf16 v[26:29], v[130:133], v[206:209], v[26:29]
	v_mfma_f32_16x16x32_bf16 v[14:17], v[114:117], v[234:237], v[14:17]
	v_mfma_f32_16x16x32_bf16 v[10:13], v[130:133], v[234:237], v[10:13]
	v_mfma_f32_16x16x32_bf16 v[54:57], v[146:149], v[162:165], v[54:57]
	v_mfma_f32_16x16x32_bf16 v[50:53], v[154:157], v[162:165], v[50:53]
	v_mfma_f32_16x16x32_bf16 v[38:41], v[146:149], v[190:193], v[38:41]
	v_mfma_f32_16x16x32_bf16 v[34:37], v[154:157], v[190:193], v[34:37]
	v_mfma_f32_16x16x32_bf16 v[22:25], v[146:149], v[202:205], v[22:25]
	v_mfma_f32_16x16x32_bf16 v[18:21], v[154:157], v[202:205], v[18:21]
	v_mfma_f32_16x16x32_bf16 v[6:9], v[146:149], v[214:217], v[6:9]
	v_mfma_f32_16x16x32_bf16 v[2:5], v[154:157], v[214:217], v[2:5]
	v_mfma_f32_16x16x32_bf16 v[54:57], v[150:153], v[186:189], v[54:57]
	v_mfma_f32_16x16x32_bf16 v[50:53], v[158:161], v[186:189], v[50:53]
	v_mfma_f32_16x16x32_bf16 v[38:41], v[150:153], v[198:201], v[38:41]
	v_mfma_f32_16x16x32_bf16 v[34:37], v[158:161], v[198:201], v[34:37]
	v_mfma_f32_16x16x32_bf16 v[22:25], v[150:153], v[206:209], v[22:25]
	v_mfma_f32_16x16x32_bf16 v[18:21], v[158:161], v[206:209], v[18:21]
	v_mfma_f32_16x16x32_bf16 v[6:9], v[150:153], v[234:237], v[6:9]
	v_mfma_f32_16x16x32_bf16 v[2:5], v[158:161], v[234:237], v[2:5]
	s_setprio 0
	s_barrier
	s_add_i32 s24, 0, 0x18000
	s_add_i32 s25, 0, 0x1c000
	v_add_u32_e32 v130, s24, v194
	v_add_u32_e32 v158, s25, v194
	ds_read_b128 v[110:113], v130
	ds_read_b128 v[114:117], v130 offset:1024
	ds_read_b128 v[122:125], v130 offset:2048
	ds_read_b128 v[130:133], v130 offset:3072
	ds_read_b128 v[146:149], v158
	ds_read_b128 v[150:153], v158 offset:1024
	ds_read_b128 v[154:157], v158 offset:2048
	ds_read_b128 v[158:161], v158 offset:3072
	s_mov_b32 m0, s28
	v_lshl_add_u64 v[240:241], v[238:239], 0, s[96:97]
	ds_read_b128 v[162:165], v196 offset:32768
	ds_read_b128 v[186:189], v196 offset:33792
	ds_read_b128 v[190:193], v196 offset:34816
	ds_read_b128 v[198:201], v196 offset:35840
	ds_read_b128 v[202:205], v196 offset:36864
	ds_read_b128 v[206:209], v196 offset:37888
	ds_read_b128 v[214:217], v196 offset:38912
	ds_read_b128 v[234:237], v196 offset:39936
	global_load_lds_dwordx4 v[240:241], off
	v_lshl_add_u64 v[240:241], v[238:239], 0, s[86:87]
	s_mov_b32 m0, s29
	s_nop 0
	global_load_lds_dwordx4 v[240:241], off
	s_waitcnt vmcnt(8)
	s_waitcnt lgkmcnt(0)
	s_barrier
	s_setprio 3
	v_mfma_f32_16x16x32_bf16 v[142:145], v[110:113], v[162:165], v[142:145]
	v_mfma_f32_16x16x32_bf16 v[138:141], v[122:125], v[162:165], v[138:141]
	v_mfma_f32_16x16x32_bf16 v[118:121], v[110:113], v[190:193], v[118:121]
	v_mfma_f32_16x16x32_bf16 v[106:109], v[122:125], v[190:193], v[106:109]
	v_mfma_f32_16x16x32_bf16 v[94:97], v[110:113], v[202:205], v[94:97]
	v_mfma_f32_16x16x32_bf16 v[90:93], v[122:125], v[202:205], v[90:93]
	v_mfma_f32_16x16x32_bf16 v[78:81], v[110:113], v[214:217], v[78:81]
	v_mfma_f32_16x16x32_bf16 v[74:77], v[122:125], v[214:217], v[74:77]
	v_mfma_f32_16x16x32_bf16 v[142:145], v[114:117], v[186:189], v[142:145]
	v_mfma_f32_16x16x32_bf16 v[138:141], v[130:133], v[186:189], v[138:141]
	v_mfma_f32_16x16x32_bf16 v[118:121], v[114:117], v[198:201], v[118:121]
	v_mfma_f32_16x16x32_bf16 v[106:109], v[130:133], v[198:201], v[106:109]
	v_mfma_f32_16x16x32_bf16 v[94:97], v[114:117], v[206:209], v[94:97]
	v_mfma_f32_16x16x32_bf16 v[90:93], v[130:133], v[206:209], v[90:93]
	v_mfma_f32_16x16x32_bf16 v[78:81], v[114:117], v[234:237], v[78:81]
	v_mfma_f32_16x16x32_bf16 v[74:77], v[130:133], v[234:237], v[74:77]
	v_mfma_f32_16x16x32_bf16 v[134:137], v[146:149], v[162:165], v[134:137]
	v_mfma_f32_16x16x32_bf16 v[126:129], v[154:157], v[162:165], v[126:129]
	v_mfma_f32_16x16x32_bf16 v[102:105], v[146:149], v[190:193], v[102:105]
	v_mfma_f32_16x16x32_bf16 v[98:101], v[154:157], v[190:193], v[98:101]
	v_mfma_f32_16x16x32_bf16 v[86:89], v[146:149], v[202:205], v[86:89]
	v_mfma_f32_16x16x32_bf16 v[82:85], v[154:157], v[202:205], v[82:85]
	v_mfma_f32_16x16x32_bf16 v[70:73], v[146:149], v[214:217], v[70:73]
	v_mfma_f32_16x16x32_bf16 v[66:69], v[154:157], v[214:217], v[66:69]
	v_mfma_f32_16x16x32_bf16 v[134:137], v[150:153], v[186:189], v[134:137]
	v_mfma_f32_16x16x32_bf16 v[126:129], v[158:161], v[186:189], v[126:129]
	v_mfma_f32_16x16x32_bf16 v[102:105], v[150:153], v[198:201], v[102:105]
	v_mfma_f32_16x16x32_bf16 v[98:101], v[158:161], v[198:201], v[98:101]
	v_mfma_f32_16x16x32_bf16 v[86:89], v[150:153], v[206:209], v[86:89]
	v_mfma_f32_16x16x32_bf16 v[82:85], v[158:161], v[206:209], v[82:85]
	v_mfma_f32_16x16x32_bf16 v[70:73], v[150:153], v[234:237], v[70:73]
	v_mfma_f32_16x16x32_bf16 v[66:69], v[158:161], v[234:237], v[66:69]
	s_setprio 0
	s_barrier
	s_add_i32 s24, s24, s17
	v_lshl_add_u64 v[240:241], v[218:219], 0, s[64:65]
	s_mov_b32 m0, s24
	ds_read_b128 v[162:165], v196 offset:49152
	ds_read_b128 v[186:189], v196 offset:50176
	ds_read_b128 v[190:193], v196 offset:51200
	ds_read_b128 v[198:201], v196 offset:52224
	ds_read_b128 v[202:205], v196 offset:53248
	ds_read_b128 v[206:209], v196 offset:54272
	ds_read_b128 v[214:217], v196 offset:55296
	ds_read_b128 v[234:237], v196 offset:56320
	global_load_lds_dwordx4 v[240:241], off
	v_lshl_add_u64 v[240:241], v[218:219], 0, s[62:63]
	s_add_i32 m0, s24, 0x2000
	s_add_i32 s24, s25, s17
	global_load_lds_dwordx4 v[240:241], off
	v_lshl_add_u64 v[240:241], v[218:219], 0, s[56:57]
	s_mov_b32 m0, s24
	v_lshl_add_u64 v[218:219], v[218:219], 0, s[58:59]
	global_load_lds_dwordx4 v[240:241], off
	s_add_i32 m0, s24, 0x2000
	s_nop 0
	global_load_lds_dwordx4 v[218:219], off
	v_lshl_add_u64 v[218:219], v[238:239], 0, s[66:67]
	s_mov_b32 m0, s35
	s_nop 0
	global_load_lds_dwordx4 v[218:219], off
	v_lshl_add_u64 v[218:219], v[238:239], 0, s[54:55]
	s_mov_b32 m0, s36
	s_nop 0
	global_load_lds_dwordx4 v[218:219], off
	s_waitcnt vmcnt(8)
	s_waitcnt lgkmcnt(0)
	s_barrier
	s_setprio 3
	v_mfma_f32_16x16x32_bf16 v[62:65], v[110:113], v[162:165], v[62:65]
	v_mfma_f32_16x16x32_bf16 v[58:61], v[122:125], v[162:165], v[58:61]
	v_mfma_f32_16x16x32_bf16 v[46:49], v[110:113], v[190:193], v[46:49]
	v_mfma_f32_16x16x32_bf16 v[42:45], v[122:125], v[190:193], v[42:45]
	v_mfma_f32_16x16x32_bf16 v[30:33], v[110:113], v[202:205], v[30:33]
	v_mfma_f32_16x16x32_bf16 v[26:29], v[122:125], v[202:205], v[26:29]
	v_mfma_f32_16x16x32_bf16 v[14:17], v[110:113], v[214:217], v[14:17]
	v_mfma_f32_16x16x32_bf16 v[10:13], v[122:125], v[214:217], v[10:13]
	v_mfma_f32_16x16x32_bf16 v[62:65], v[114:117], v[186:189], v[62:65]
	v_mfma_f32_16x16x32_bf16 v[58:61], v[130:133], v[186:189], v[58:61]
	v_mfma_f32_16x16x32_bf16 v[46:49], v[114:117], v[198:201], v[46:49]
	v_mfma_f32_16x16x32_bf16 v[42:45], v[130:133], v[198:201], v[42:45]
	v_mfma_f32_16x16x32_bf16 v[30:33], v[114:117], v[206:209], v[30:33]
	v_mfma_f32_16x16x32_bf16 v[26:29], v[130:133], v[206:209], v[26:29]
	v_mfma_f32_16x16x32_bf16 v[14:17], v[114:117], v[234:237], v[14:17]
	v_mfma_f32_16x16x32_bf16 v[10:13], v[130:133], v[234:237], v[10:13]
	v_mfma_f32_16x16x32_bf16 v[54:57], v[146:149], v[162:165], v[54:57]
	v_mfma_f32_16x16x32_bf16 v[50:53], v[154:157], v[162:165], v[50:53]
	v_mfma_f32_16x16x32_bf16 v[38:41], v[146:149], v[190:193], v[38:41]
	v_mfma_f32_16x16x32_bf16 v[34:37], v[154:157], v[190:193], v[34:37]
	v_mfma_f32_16x16x32_bf16 v[22:25], v[146:149], v[202:205], v[22:25]
	v_mfma_f32_16x16x32_bf16 v[18:21], v[154:157], v[202:205], v[18:21]
	v_mfma_f32_16x16x32_bf16 v[6:9], v[146:149], v[214:217], v[6:9]
	v_mfma_f32_16x16x32_bf16 v[2:5], v[154:157], v[214:217], v[2:5]
	v_mfma_f32_16x16x32_bf16 v[54:57], v[150:153], v[186:189], v[54:57]
	v_mfma_f32_16x16x32_bf16 v[50:53], v[158:161], v[186:189], v[50:53]
	v_mfma_f32_16x16x32_bf16 v[38:41], v[150:153], v[198:201], v[38:41]
	v_mfma_f32_16x16x32_bf16 v[34:37], v[158:161], v[198:201], v[34:37]
	v_mfma_f32_16x16x32_bf16 v[22:25], v[150:153], v[206:209], v[22:25]
	v_mfma_f32_16x16x32_bf16 v[18:21], v[158:161], v[206:209], v[18:21]
	v_mfma_f32_16x16x32_bf16 v[6:9], v[150:153], v[234:237], v[6:9]
	v_mfma_f32_16x16x32_bf16 v[2:5], v[158:161], v[234:237], v[2:5]
	s_setprio 0
	s_barrier
	s_add_i32 s43, s43, 2
	s_add_u32 s40, s40, 0x10000
	s_addc_u32 s41, s41, 0
	s_add_u32 s22, s22, 0x100
	s_addc_u32 s23, s23, 0
	s_cmp_gt_u32 s43, 13
	s_cbranch_scc0 .LBB0_1083
	s_and_b64 vcc, exec, s[8:9]
	s_movk_i32 s43, 0x1000
	s_cbranch_vccz .LBB0_1086
	s_barrier

.LBB0_1243:
	s_add_u32 s4, s14, 0xfffbe080
	s_addc_u32 s5, s15, -1
	s_add_i32 s2, 0, 0x10000
	s_cmp_eq_u32 s51, 12
	s_cselect_b32 s39, s31, s5
	s_cselect_b32 s38, s69, s4
	s_cselect_b32 s5, s29, s50
	s_cselect_b32 s4, vcc_lo, vcc_hi
	s_add_i32 s44, 0, 0x14000
	v_add_u32_e32 v144, s2, v193
	v_add_u32_e32 v182, s44, v193
	ds_read_b128 v[132:135], v144
	ds_read_b128 v[136:139], v144 offset:1024
	ds_read_b128 v[140:143], v144 offset:2048
	ds_read_b128 v[144:147], v144 offset:3072
	ds_read_b128 v[148:151], v182
	ds_read_b128 v[152:155], v182 offset:1024
	ds_read_b128 v[178:181], v182 offset:2048
	ds_read_b128 v[182:185], v182 offset:3072
	s_mov_b32 s40, 0xfffc0000
	v_lshl_add_u64 v[190:191], s[14:15], 0, v[176:177]
	s_mov_b32 s41, -1
	v_lshl_add_u64 v[208:209], v[190:191], 0, s[40:41]
	s_add_i32 m0, s25, 0xc000
	ds_read_b128 v[186:189], v199
	ds_read_b128 v[200:203], v199 offset:1024
	ds_read_b128 v[204:207], v199 offset:2048
	ds_read_b128 v[214:217], v199 offset:3072
	ds_read_b128 v[234:237], v199 offset:4096
	ds_read_b128 v[238:241], v199 offset:5120
	ds_read_b128 v[242:245], v199 offset:6144
	ds_read_b128 v[246:249], v199 offset:7168
	global_load_lds_dwordx4 v[208:209], off
	s_add_i32 m0, s25, 0xe000
	s_nop 0
	global_load_lds_dwordx4 v[190:191], off
	s_waitcnt vmcnt(8)
	s_waitcnt lgkmcnt(0)
	s_barrier
	s_setprio 3
	v_mfma_f32_16x16x32_bf16 v[64:67], v[132:135], v[186:189], v[64:67]
	v_mfma_f32_16x16x32_bf16 v[56:59], v[140:143], v[186:189], v[56:59]
	v_mfma_f32_16x16x32_bf16 v[60:63], v[132:135], v[204:207], v[60:63]
	v_mfma_f32_16x16x32_bf16 v[20:23], v[140:143], v[204:207], v[20:23]
	v_mfma_f32_16x16x32_bf16 v[128:131], v[132:135], v[234:237], v[128:131]
	v_mfma_f32_16x16x32_bf16 v[96:99], v[140:143], v[234:237], v[96:99]
	v_mfma_f32_16x16x32_bf16 v[124:127], v[132:135], v[242:245], v[124:127]
	v_mfma_f32_16x16x32_bf16 v[92:95], v[140:143], v[242:245], v[92:95]
	v_mfma_f32_16x16x32_bf16 v[64:67], v[136:139], v[200:203], v[64:67]
	v_mfma_f32_16x16x32_bf16 v[56:59], v[144:147], v[200:203], v[56:59]
	v_mfma_f32_16x16x32_bf16 v[60:63], v[136:139], v[214:217], v[60:63]
	v_mfma_f32_16x16x32_bf16 v[20:23], v[144:147], v[214:217], v[20:23]
	v_mfma_f32_16x16x32_bf16 v[128:131], v[136:139], v[238:241], v[128:131]
	v_mfma_f32_16x16x32_bf16 v[96:99], v[144:147], v[238:241], v[96:99]
	v_mfma_f32_16x16x32_bf16 v[124:127], v[136:139], v[246:249], v[124:127]
	v_mfma_f32_16x16x32_bf16 v[92:95], v[144:147], v[246:249], v[92:95]
	v_mfma_f32_16x16x32_bf16 v[48:51], v[148:151], v[186:189], v[48:51]
	v_mfma_f32_16x16x32_bf16 v[4:7], v[178:181], v[186:189], v[4:7]
	v_mfma_f32_16x16x32_bf16 v[44:47], v[148:151], v[204:207], v[44:47]
	v_mfma_f32_16x16x32_bf16 v[8:11], v[178:181], v[204:207], v[8:11]
	v_mfma_f32_16x16x32_bf16 v[120:123], v[148:151], v[234:237], v[120:123]
	v_mfma_f32_16x16x32_bf16 v[88:91], v[178:181], v[234:237], v[88:91]
	v_mfma_f32_16x16x32_bf16 v[112:115], v[148:151], v[242:245], v[112:115]
	v_mfma_f32_16x16x32_bf16 v[80:83], v[178:181], v[242:245], v[80:83]
	v_mfma_f32_16x16x32_bf16 v[48:51], v[152:155], v[200:203], v[48:51]
	v_mfma_f32_16x16x32_bf16 v[4:7], v[182:185], v[200:203], v[4:7]
	v_mfma_f32_16x16x32_bf16 v[44:47], v[152:155], v[214:217], v[44:47]
	v_mfma_f32_16x16x32_bf16 v[8:11], v[182:185], v[214:217], v[8:11]
	v_mfma_f32_16x16x32_bf16 v[120:123], v[152:155], v[238:241], v[120:123]
	v_mfma_f32_16x16x32_bf16 v[88:91], v[182:185], v[238:241], v[88:91]
	v_mfma_f32_16x16x32_bf16 v[112:115], v[152:155], v[246:249], v[112:115]
	v_mfma_f32_16x16x32_bf16 v[80:83], v[182:185], v[246:249], v[80:83]
	s_setprio 0
	s_barrier
	s_add_i32 s2, s2, s72
	v_lshl_add_u64 v[190:191], s[4:5], 0, v[0:1]
	s_mov_b32 m0, s2
	ds_read_b128 v[186:189], v199 offset:16384
	ds_read_b128 v[200:203], v199 offset:17408
	ds_read_b128 v[204:207], v199 offset:18432
	ds_read_b128 v[214:217], v199 offset:19456
	ds_read_b128 v[234:237], v199 offset:20480
	ds_read_b128 v[238:241], v199 offset:21504
	ds_read_b128 v[242:245], v199 offset:22528
	ds_read_b128 v[246:249], v199 offset:23552
	global_load_lds_dwordx4 v[190:191], off
	v_lshl_add_u64 v[208:209], v[190:191], 0, s[88:89]
	s_add_i32 m0, s2, 0x2000
	s_add_i32 s2, s44, s72
	global_load_lds_dwordx4 v[208:209], off
	v_lshl_add_u64 v[208:209], v[190:191], 0, s[90:91]
	s_mov_b32 m0, s2
	s_nop 0
	global_load_lds_dwordx4 v[208:209], off
	v_lshl_add_u64 v[208:209], v[190:191], 0, s[92:93]
	s_add_i32 m0, s2, 0x2000
	s_nop 0
	global_load_lds_dwordx4 v[208:209], off
	v_lshl_add_u64 v[208:209], s[38:39], 0, v[162:163]
	s_mov_b32 m0, s25
	v_lshl_add_u64 v[218:219], v[208:209], 0, s[96:97]
	global_load_lds_dwordx4 v[208:209], off
	s_mov_b32 m0, s78
	s_nop 0
	global_load_lds_dwordx4 v[218:219], off
	s_waitcnt vmcnt(8)
	s_waitcnt lgkmcnt(0)
	s_barrier
	s_setprio 3
	v_mfma_f32_16x16x32_bf16 v[116:119], v[132:135], v[186:189], v[116:119]
	v_mfma_f32_16x16x32_bf16 v[84:87], v[140:143], v[186:189], v[84:87]
	v_mfma_f32_16x16x32_bf16 v[108:111], v[132:135], v[204:207], v[108:111]
	v_mfma_f32_16x16x32_bf16 v[76:79], v[140:143], v[204:207], v[76:79]
	v_mfma_f32_16x16x32_bf16 v[52:55], v[132:135], v[234:237], v[52:55]
	v_mfma_f32_16x16x32_bf16 v[36:39], v[140:143], v[234:237], v[36:39]
	v_mfma_f32_16x16x32_bf16 v[40:43], v[132:135], v[242:245], v[40:43]
	v_mfma_f32_16x16x32_bf16 v[28:31], v[140:143], v[242:245], v[28:31]
	v_mfma_f32_16x16x32_bf16 v[116:119], v[136:139], v[200:203], v[116:119]
	v_mfma_f32_16x16x32_bf16 v[84:87], v[144:147], v[200:203], v[84:87]
	v_mfma_f32_16x16x32_bf16 v[108:111], v[136:139], v[214:217], v[108:111]
	v_mfma_f32_16x16x32_bf16 v[76:79], v[144:147], v[214:217], v[76:79]
	v_mfma_f32_16x16x32_bf16 v[52:55], v[136:139], v[238:241], v[52:55]
	v_mfma_f32_16x16x32_bf16 v[36:39], v[144:147], v[238:241], v[36:39]
	v_mfma_f32_16x16x32_bf16 v[40:43], v[136:139], v[246:249], v[40:43]
	v_mfma_f32_16x16x32_bf16 v[28:31], v[144:147], v[246:249], v[28:31]
	v_mfma_f32_16x16x32_bf16 v[104:107], v[148:151], v[186:189], v[104:107]
	v_mfma_f32_16x16x32_bf16 v[72:75], v[178:181], v[186:189], v[72:75]
	v_mfma_f32_16x16x32_bf16 v[100:103], v[148:151], v[204:207], v[100:103]
	v_mfma_f32_16x16x32_bf16 v[68:71], v[178:181], v[204:207], v[68:71]
	v_mfma_f32_16x16x32_bf16 v[32:35], v[148:151], v[234:237], v[32:35]
	v_mfma_f32_16x16x32_bf16 v[12:15], v[178:181], v[234:237], v[12:15]
	v_mfma_f32_16x16x32_bf16 v[24:27], v[148:151], v[242:245], v[24:27]
	v_mfma_f32_16x16x32_bf16 v[16:19], v[178:181], v[242:245], v[16:19]
	v_mfma_f32_16x16x32_bf16 v[104:107], v[152:155], v[200:203], v[104:107]
	v_mfma_f32_16x16x32_bf16 v[72:75], v[182:185], v[200:203], v[72:75]
	v_mfma_f32_16x16x32_bf16 v[100:103], v[152:155], v[214:217], v[100:103]
	v_mfma_f32_16x16x32_bf16 v[68:71], v[182:185], v[214:217], v[68:71]
	v_mfma_f32_16x16x32_bf16 v[32:35], v[152:155], v[238:241], v[32:35]
	v_mfma_f32_16x16x32_bf16 v[12:15], v[182:185], v[238:241], v[12:15]
	v_mfma_f32_16x16x32_bf16 v[24:27], v[152:155], v[246:249], v[24:27]
	v_mfma_f32_16x16x32_bf16 v[16:19], v[182:185], v[246:249], v[16:19]
	s_setprio 0
	s_barrier
	s_add_i32 s2, 0, 0x18000
	s_add_i32 s4, 0, 0x1c000
	v_add_u32_e32 v144, s2, v193
	v_add_u32_e32 v182, s4, v193
	ds_read_b128 v[132:135], v144
	ds_read_b128 v[136:139], v144 offset:1024
	ds_read_b128 v[140:143], v144 offset:2048
	ds_read_b128 v[144:147], v144 offset:3072
	ds_read_b128 v[148:151], v182
	ds_read_b128 v[152:155], v182 offset:1024
	ds_read_b128 v[178:181], v182 offset:2048
	ds_read_b128 v[182:185], v182 offset:3072
	s_mov_b32 m0, s79
	v_lshl_add_u64 v[218:219], v[208:209], 0, s[88:89]
	ds_read_b128 v[186:189], v199 offset:32768
	ds_read_b128 v[200:203], v199 offset:33792
	ds_read_b128 v[204:207], v199 offset:34816
	ds_read_b128 v[214:217], v199 offset:35840
	ds_read_b128 v[234:237], v199 offset:36864
	ds_read_b128 v[238:241], v199 offset:37888
	ds_read_b128 v[242:245], v199 offset:38912
	ds_read_b128 v[246:249], v199 offset:39936
	global_load_lds_dwordx4 v[218:219], off
	v_lshl_add_u64 v[218:219], v[208:209], 0, s[52:53]
	s_mov_b32 m0, s6
	s_nop 0
	global_load_lds_dwordx4 v[218:219], off
	s_waitcnt vmcnt(8)
	s_waitcnt lgkmcnt(0)
	s_barrier
	s_setprio 3
	v_mfma_f32_16x16x32_bf16 v[64:67], v[132:135], v[186:189], v[64:67]
	v_mfma_f32_16x16x32_bf16 v[56:59], v[140:143], v[186:189], v[56:59]
	v_mfma_f32_16x16x32_bf16 v[60:63], v[132:135], v[204:207], v[60:63]
	v_mfma_f32_16x16x32_bf16 v[20:23], v[140:143], v[204:207], v[20:23]
	v_mfma_f32_16x16x32_bf16 v[128:131], v[132:135], v[234:237], v[128:131]
	v_mfma_f32_16x16x32_bf16 v[96:99], v[140:143], v[234:237], v[96:99]
	v_mfma_f32_16x16x32_bf16 v[124:127], v[132:135], v[242:245], v[124:127]
	v_mfma_f32_16x16x32_bf16 v[92:95], v[140:143], v[242:245], v[92:95]
	v_mfma_f32_16x16x32_bf16 v[64:67], v[136:139], v[200:203], v[64:67]
	v_mfma_f32_16x16x32_bf16 v[56:59], v[144:147], v[200:203], v[56:59]
	v_mfma_f32_16x16x32_bf16 v[60:63], v[136:139], v[214:217], v[60:63]
	v_mfma_f32_16x16x32_bf16 v[20:23], v[144:147], v[214:217], v[20:23]
	v_mfma_f32_16x16x32_bf16 v[128:131], v[136:139], v[238:241], v[128:131]
	v_mfma_f32_16x16x32_bf16 v[96:99], v[144:147], v[238:241], v[96:99]
	v_mfma_f32_16x16x32_bf16 v[124:127], v[136:139], v[246:249], v[124:127]
	v_mfma_f32_16x16x32_bf16 v[92:95], v[144:147], v[246:249], v[92:95]
	v_mfma_f32_16x16x32_bf16 v[48:51], v[148:151], v[186:189], v[48:51]
	v_mfma_f32_16x16x32_bf16 v[4:7], v[178:181], v[186:189], v[4:7]
	v_mfma_f32_16x16x32_bf16 v[44:47], v[148:151], v[204:207], v[44:47]
	v_mfma_f32_16x16x32_bf16 v[8:11], v[178:181], v[204:207], v[8:11]
	v_mfma_f32_16x16x32_bf16 v[120:123], v[148:151], v[234:237], v[120:123]
	v_mfma_f32_16x16x32_bf16 v[88:91], v[178:181], v[234:237], v[88:91]
	v_mfma_f32_16x16x32_bf16 v[112:115], v[148:151], v[242:245], v[112:115]
	v_mfma_f32_16x16x32_bf16 v[80:83], v[178:181], v[242:245], v[80:83]
	v_mfma_f32_16x16x32_bf16 v[48:51], v[152:155], v[200:203], v[48:51]
	v_mfma_f32_16x16x32_bf16 v[4:7], v[182:185], v[200:203], v[4:7]
	v_mfma_f32_16x16x32_bf16 v[44:47], v[152:155], v[214:217], v[44:47]
	v_mfma_f32_16x16x32_bf16 v[8:11], v[182:185], v[214:217], v[8:11]
	v_mfma_f32_16x16x32_bf16 v[120:123], v[152:155], v[238:241], v[120:123]
	v_mfma_f32_16x16x32_bf16 v[88:91], v[182:185], v[238:241], v[88:91]
	v_mfma_f32_16x16x32_bf16 v[112:115], v[152:155], v[246:249], v[112:115]
	v_mfma_f32_16x16x32_bf16 v[80:83], v[182:185], v[246:249], v[80:83]
	s_setprio 0
	s_barrier
	s_add_i32 s2, s2, s72
	v_lshl_add_u64 v[218:219], v[190:191], 0, s[64:65]
	s_mov_b32 m0, s2
	ds_read_b128 v[186:189], v199 offset:49152
	ds_read_b128 v[200:203], v199 offset:50176
	ds_read_b128 v[204:207], v199 offset:51200
	ds_read_b128 v[214:217], v199 offset:52224
	ds_read_b128 v[234:237], v199 offset:53248
	ds_read_b128 v[238:241], v199 offset:54272
	ds_read_b128 v[242:245], v199 offset:55296
	ds_read_b128 v[246:249], v199 offset:56320
	global_load_lds_dwordx4 v[218:219], off
	v_lshl_add_u64 v[218:219], v[190:191], 0, s[62:63]
	s_add_i32 m0, s2, 0x2000
	s_add_i32 s2, s4, s72
	global_load_lds_dwordx4 v[218:219], off
	v_lshl_add_u64 v[218:219], v[190:191], 0, s[56:57]
	s_mov_b32 m0, s2
	v_lshl_add_u64 v[190:191], v[190:191], 0, s[58:59]
	global_load_lds_dwordx4 v[218:219], off
	s_add_i32 m0, s2, 0x2000
	s_nop 0
	global_load_lds_dwordx4 v[190:191], off
	v_lshl_add_u64 v[190:191], v[208:209], 0, s[66:67]
	s_mov_b32 m0, s7
	s_nop 0
	global_load_lds_dwordx4 v[190:191], off
	v_lshl_add_u64 v[190:191], v[208:209], 0, s[70:71]
	s_mov_b32 m0, s16
	s_nop 0
	global_load_lds_dwordx4 v[190:191], off
	s_waitcnt vmcnt(8)
	s_waitcnt lgkmcnt(0)
	s_barrier
	s_setprio 3
	v_mfma_f32_16x16x32_bf16 v[116:119], v[132:135], v[186:189], v[116:119]
	v_mfma_f32_16x16x32_bf16 v[84:87], v[140:143], v[186:189], v[84:87]
	v_mfma_f32_16x16x32_bf16 v[108:111], v[132:135], v[204:207], v[108:111]
	v_mfma_f32_16x16x32_bf16 v[76:79], v[140:143], v[204:207], v[76:79]
	v_mfma_f32_16x16x32_bf16 v[52:55], v[132:135], v[234:237], v[52:55]
	v_mfma_f32_16x16x32_bf16 v[36:39], v[140:143], v[234:237], v[36:39]
	v_mfma_f32_16x16x32_bf16 v[40:43], v[132:135], v[242:245], v[40:43]
	v_mfma_f32_16x16x32_bf16 v[28:31], v[140:143], v[242:245], v[28:31]
	v_mfma_f32_16x16x32_bf16 v[116:119], v[136:139], v[200:203], v[116:119]
	v_mfma_f32_16x16x32_bf16 v[84:87], v[144:147], v[200:203], v[84:87]
	v_mfma_f32_16x16x32_bf16 v[108:111], v[136:139], v[214:217], v[108:111]
	v_mfma_f32_16x16x32_bf16 v[76:79], v[144:147], v[214:217], v[76:79]
	v_mfma_f32_16x16x32_bf16 v[52:55], v[136:139], v[238:241], v[52:55]
	v_mfma_f32_16x16x32_bf16 v[36:39], v[144:147], v[238:241], v[36:39]
	v_mfma_f32_16x16x32_bf16 v[40:43], v[136:139], v[246:249], v[40:43]
	v_mfma_f32_16x16x32_bf16 v[28:31], v[144:147], v[246:249], v[28:31]
	v_mfma_f32_16x16x32_bf16 v[104:107], v[148:151], v[186:189], v[104:107]
	v_mfma_f32_16x16x32_bf16 v[72:75], v[178:181], v[186:189], v[72:75]
	v_mfma_f32_16x16x32_bf16 v[100:103], v[148:151], v[204:207], v[100:103]
	v_mfma_f32_16x16x32_bf16 v[68:71], v[178:181], v[204:207], v[68:71]
	v_mfma_f32_16x16x32_bf16 v[32:35], v[148:151], v[234:237], v[32:35]
	v_mfma_f32_16x16x32_bf16 v[12:15], v[178:181], v[234:237], v[12:15]
	v_mfma_f32_16x16x32_bf16 v[24:27], v[148:151], v[242:245], v[24:27]
	v_mfma_f32_16x16x32_bf16 v[16:19], v[178:181], v[242:245], v[16:19]
	v_mfma_f32_16x16x32_bf16 v[104:107], v[152:155], v[200:203], v[104:107]
	v_mfma_f32_16x16x32_bf16 v[72:75], v[182:185], v[200:203], v[72:75]
	v_mfma_f32_16x16x32_bf16 v[100:103], v[152:155], v[214:217], v[100:103]
	v_mfma_f32_16x16x32_bf16 v[68:71], v[182:185], v[214:217], v[68:71]
	v_mfma_f32_16x16x32_bf16 v[32:35], v[152:155], v[238:241], v[32:35]
	v_mfma_f32_16x16x32_bf16 v[12:15], v[182:185], v[238:241], v[12:15]
	v_mfma_f32_16x16x32_bf16 v[24:27], v[152:155], v[246:249], v[24:27]
	v_mfma_f32_16x16x32_bf16 v[16:19], v[182:185], v[246:249], v[16:19]
	s_setprio 0
	s_barrier
	s_add_i32 s51, s51, 2
	s_add_u32 vcc_hi, vcc_hi, 0x10000
	s_addc_u32 s50, s50, 0
	s_add_u32 s14, s14, 0x100
	s_addc_u32 s15, s15, 0
	s_cmp_gt_u32 s51, 13
	s_cbranch_scc0 .LBB0_1243
	v_lshl_or_b32 v178, s68, 7, v198
	v_mov_b32_e32 v179, 0
	v_lshlrev_b32_e32 v180, 2, v178
	v_mov_b32_e32 v181, 0
	v_lshl_add_u64 v[182:183], v[164:165], 0, v[180:181]
	global_load_dwordx4 v[132:135], v[182:183], off
	global_load_dwordx4 v[234:237], v[182:183], off offset:16
	v_lshl_add_u64 v[184:185], v[166:167], 0, v[180:181]
	global_load_dwordx4 v[136:139], v[184:185], off
	global_load_dwordx4 v[238:241], v[184:185], off offset:16
	v_lshl_add_u64 v[186:187], v[168:169], 0, v[180:181]
	global_load_dwordx4 v[140:143], v[186:187], off
	global_load_dwordx4 v[242:245], v[186:187], off offset:16
	v_lshl_add_u64 v[188:189], v[170:171], 0, v[180:181]
	global_load_dwordx4 v[144:147], v[188:189], off
	global_load_dwordx4 v[246:249], v[188:189], off offset:16
	v_lshl_add_u64 v[190:191], v[172:173], 0, v[180:181]
	global_load_dwordx4 v[148:151], v[190:191], off
	global_load_dwordx4 v[200:203], v[190:191], off offset:16
	v_lshl_add_u64 v[208:209], v[174:175], 0, v[180:181]
	global_load_dwordx4 v[152:155], v[208:209], off
	global_load_dwordx4 v[204:207], v[208:209], off offset:16
	s_and_b64 vcc, exec, s[26:27]
	s_cbranch_vccz .LBB0_1246
	s_barrier

.LBB0_1455:
	s_add_u32 s20, s14, 0xfff50080
	s_addc_u32 s21, s15, -1
	s_add_i32 s40, 0, 0x10000
	s_cmp_eq_u32 s37, 40
	s_cselect_b32 s21, s9, s21
	s_cselect_b32 s20, s8, s20
	s_cselect_b32 s39, s13, s36
	s_cselect_b32 s38, s12, s19
	s_add_i32 s41, 0, 0x14000
	v_add_u32_e32 v130, s40, v194
	v_add_u32_e32 v158, s41, v194
	ds_read_b128 v[110:113], v130
	ds_read_b128 v[114:117], v130 offset:1024
	ds_read_b128 v[122:125], v130 offset:2048
	ds_read_b128 v[130:133], v130 offset:3072
	ds_read_b128 v[146:149], v158
	ds_read_b128 v[150:153], v158 offset:1024
	ds_read_b128 v[154:157], v158 offset:2048
	ds_read_b128 v[158:161], v158 offset:3072
	v_lshl_add_u64 v[218:219], s[14:15], 0, v[184:185]
	s_add_i32 m0, s17, 0xc000
	ds_read_b128 v[162:165], v196
	ds_read_b128 v[186:189], v196 offset:1024
	ds_read_b128 v[190:193], v196 offset:2048
	ds_read_b128 v[198:201], v196 offset:3072
	ds_read_b128 v[202:205], v196 offset:4096
	ds_read_b128 v[206:209], v196 offset:5120
	ds_read_b128 v[214:217], v196 offset:6144
	ds_read_b128 v[234:237], v196 offset:7168
	global_load_lds_dwordx4 v[218:219], off
	v_lshl_add_u64 v[218:219], v[218:219], 0, s[76:77]
	s_add_i32 m0, s17, 0xe000
	s_nop 0
	global_load_lds_dwordx4 v[218:219], off
	s_waitcnt vmcnt(8)
	s_waitcnt lgkmcnt(0)
	s_barrier
	s_setprio 3
	v_mfma_f32_16x16x32_bf16 v[142:145], v[110:113], v[162:165], v[142:145]
	v_mfma_f32_16x16x32_bf16 v[138:141], v[122:125], v[162:165], v[138:141]
	v_mfma_f32_16x16x32_bf16 v[118:121], v[110:113], v[190:193], v[118:121]
	v_mfma_f32_16x16x32_bf16 v[106:109], v[122:125], v[190:193], v[106:109]
	v_mfma_f32_16x16x32_bf16 v[94:97], v[110:113], v[202:205], v[94:97]
	v_mfma_f32_16x16x32_bf16 v[90:93], v[122:125], v[202:205], v[90:93]
	v_mfma_f32_16x16x32_bf16 v[78:81], v[110:113], v[214:217], v[78:81]
	v_mfma_f32_16x16x32_bf16 v[74:77], v[122:125], v[214:217], v[74:77]
	v_mfma_f32_16x16x32_bf16 v[142:145], v[114:117], v[186:189], v[142:145]
	v_mfma_f32_16x16x32_bf16 v[138:141], v[130:133], v[186:189], v[138:141]
	v_mfma_f32_16x16x32_bf16 v[118:121], v[114:117], v[198:201], v[118:121]
	v_mfma_f32_16x16x32_bf16 v[106:109], v[130:133], v[198:201], v[106:109]
	v_mfma_f32_16x16x32_bf16 v[94:97], v[114:117], v[206:209], v[94:97]
	v_mfma_f32_16x16x32_bf16 v[90:93], v[130:133], v[206:209], v[90:93]
	v_mfma_f32_16x16x32_bf16 v[78:81], v[114:117], v[234:237], v[78:81]
	v_mfma_f32_16x16x32_bf16 v[74:77], v[130:133], v[234:237], v[74:77]
	v_mfma_f32_16x16x32_bf16 v[134:137], v[146:149], v[162:165], v[134:137]
	v_mfma_f32_16x16x32_bf16 v[126:129], v[154:157], v[162:165], v[126:129]
	v_mfma_f32_16x16x32_bf16 v[102:105], v[146:149], v[190:193], v[102:105]
	v_mfma_f32_16x16x32_bf16 v[98:101], v[154:157], v[190:193], v[98:101]
	v_mfma_f32_16x16x32_bf16 v[86:89], v[146:149], v[202:205], v[86:89]
	v_mfma_f32_16x16x32_bf16 v[82:85], v[154:157], v[202:205], v[82:85]
	v_mfma_f32_16x16x32_bf16 v[70:73], v[146:149], v[214:217], v[70:73]
	v_mfma_f32_16x16x32_bf16 v[66:69], v[154:157], v[214:217], v[66:69]
	v_mfma_f32_16x16x32_bf16 v[134:137], v[150:153], v[186:189], v[134:137]
	v_mfma_f32_16x16x32_bf16 v[126:129], v[158:161], v[186:189], v[126:129]
	v_mfma_f32_16x16x32_bf16 v[102:105], v[150:153], v[198:201], v[102:105]
	v_mfma_f32_16x16x32_bf16 v[98:101], v[158:161], v[198:201], v[98:101]
	v_mfma_f32_16x16x32_bf16 v[86:89], v[150:153], v[206:209], v[86:89]
	v_mfma_f32_16x16x32_bf16 v[82:85], v[158:161], v[206:209], v[82:85]
	v_mfma_f32_16x16x32_bf16 v[70:73], v[150:153], v[234:237], v[70:73]
	v_mfma_f32_16x16x32_bf16 v[66:69], v[158:161], v[234:237], v[66:69]
	s_setprio 0
	s_barrier
	v_lshl_add_u64 v[218:219], s[38:39], 0, v[0:1]
	s_add_i32 s38, s40, s16
	s_mov_b32 m0, s38
	ds_read_b128 v[162:165], v196 offset:16384
	ds_read_b128 v[186:189], v196 offset:17408
	ds_read_b128 v[190:193], v196 offset:18432
	ds_read_b128 v[198:201], v196 offset:19456
	ds_read_b128 v[202:205], v196 offset:20480
	ds_read_b128 v[206:209], v196 offset:21504
	ds_read_b128 v[214:217], v196 offset:22528
	ds_read_b128 v[234:237], v196 offset:23552
	global_load_lds_dwordx4 v[218:219], off
	v_lshl_add_u64 v[238:239], v[218:219], 0, s[88:89]
	s_add_i32 m0, s38, 0x2000
	s_add_i32 s38, s41, s16
	global_load_lds_dwordx4 v[238:239], off
	v_lshl_add_u64 v[238:239], v[218:219], 0, s[90:91]
	s_mov_b32 m0, s38
	s_nop 0
	global_load_lds_dwordx4 v[238:239], off
	v_lshl_add_u64 v[238:239], v[218:219], 0, s[92:93]
	s_add_i32 m0, s38, 0x2000
	s_nop 0
	global_load_lds_dwordx4 v[238:239], off
	v_lshl_add_u64 v[238:239], s[20:21], 0, v[166:167]
	s_mov_b32 m0, s17
	v_lshl_add_u64 v[240:241], v[238:239], 0, s[76:77]
	global_load_lds_dwordx4 v[238:239], off
	s_mov_b32 m0, s22
	s_nop 0
	global_load_lds_dwordx4 v[240:241], off
	s_waitcnt vmcnt(8)
	s_waitcnt lgkmcnt(0)
	s_barrier
	s_setprio 3
	v_mfma_f32_16x16x32_bf16 v[62:65], v[110:113], v[162:165], v[62:65]
	v_mfma_f32_16x16x32_bf16 v[58:61], v[122:125], v[162:165], v[58:61]
	v_mfma_f32_16x16x32_bf16 v[46:49], v[110:113], v[190:193], v[46:49]
	v_mfma_f32_16x16x32_bf16 v[42:45], v[122:125], v[190:193], v[42:45]
	v_mfma_f32_16x16x32_bf16 v[30:33], v[110:113], v[202:205], v[30:33]
	v_mfma_f32_16x16x32_bf16 v[26:29], v[122:125], v[202:205], v[26:29]
	v_mfma_f32_16x16x32_bf16 v[14:17], v[110:113], v[214:217], v[14:17]
	v_mfma_f32_16x16x32_bf16 v[10:13], v[122:125], v[214:217], v[10:13]
	v_mfma_f32_16x16x32_bf16 v[62:65], v[114:117], v[186:189], v[62:65]
	v_mfma_f32_16x16x32_bf16 v[58:61], v[130:133], v[186:189], v[58:61]
	v_mfma_f32_16x16x32_bf16 v[46:49], v[114:117], v[198:201], v[46:49]
	v_mfma_f32_16x16x32_bf16 v[42:45], v[130:133], v[198:201], v[42:45]
	v_mfma_f32_16x16x32_bf16 v[30:33], v[114:117], v[206:209], v[30:33]
	v_mfma_f32_16x16x32_bf16 v[26:29], v[130:133], v[206:209], v[26:29]
	v_mfma_f32_16x16x32_bf16 v[14:17], v[114:117], v[234:237], v[14:17]
	v_mfma_f32_16x16x32_bf16 v[10:13], v[130:133], v[234:237], v[10:13]
	v_mfma_f32_16x16x32_bf16 v[54:57], v[146:149], v[162:165], v[54:57]
	v_mfma_f32_16x16x32_bf16 v[50:53], v[154:157], v[162:165], v[50:53]
	v_mfma_f32_16x16x32_bf16 v[38:41], v[146:149], v[190:193], v[38:41]
	v_mfma_f32_16x16x32_bf16 v[34:37], v[154:157], v[190:193], v[34:37]
	v_mfma_f32_16x16x32_bf16 v[22:25], v[146:149], v[202:205], v[22:25]
	v_mfma_f32_16x16x32_bf16 v[18:21], v[154:157], v[202:205], v[18:21]
	v_mfma_f32_16x16x32_bf16 v[6:9], v[146:149], v[214:217], v[6:9]
	v_mfma_f32_16x16x32_bf16 v[2:5], v[154:157], v[214:217], v[2:5]
	v_mfma_f32_16x16x32_bf16 v[54:57], v[150:153], v[186:189], v[54:57]
	v_mfma_f32_16x16x32_bf16 v[50:53], v[158:161], v[186:189], v[50:53]
	v_mfma_f32_16x16x32_bf16 v[38:41], v[150:153], v[198:201], v[38:41]
	v_mfma_f32_16x16x32_bf16 v[34:37], v[158:161], v[198:201], v[34:37]
	v_mfma_f32_16x16x32_bf16 v[22:25], v[150:153], v[206:209], v[22:25]
	v_mfma_f32_16x16x32_bf16 v[18:21], v[158:161], v[206:209], v[18:21]
	v_mfma_f32_16x16x32_bf16 v[6:9], v[150:153], v[234:237], v[6:9]
	v_mfma_f32_16x16x32_bf16 v[2:5], v[158:161], v[234:237], v[2:5]
	s_setprio 0
	s_barrier
	s_add_i32 s20, 0, 0x18000
	s_add_i32 s21, 0, 0x1c000
	v_add_u32_e32 v130, s20, v194
	v_add_u32_e32 v158, s21, v194
	ds_read_b128 v[110:113], v130
	ds_read_b128 v[114:117], v130 offset:1024
	ds_read_b128 v[122:125], v130 offset:2048
	ds_read_b128 v[130:133], v130 offset:3072
	ds_read_b128 v[146:149], v158
	ds_read_b128 v[150:153], v158 offset:1024
	ds_read_b128 v[154:157], v158 offset:2048
	ds_read_b128 v[158:161], v158 offset:3072
	s_mov_b32 m0, s23
	v_lshl_add_u64 v[240:241], v[238:239], 0, s[60:61]
	ds_read_b128 v[162:165], v196 offset:32768
	ds_read_b128 v[186:189], v196 offset:33792
	ds_read_b128 v[190:193], v196 offset:34816
	ds_read_b128 v[198:201], v196 offset:35840
	ds_read_b128 v[202:205], v196 offset:36864
	ds_read_b128 v[206:209], v196 offset:37888
	ds_read_b128 v[214:217], v196 offset:38912
	ds_read_b128 v[234:237], v196 offset:39936
	global_load_lds_dwordx4 v[240:241], off
	v_lshl_add_u64 v[240:241], v[238:239], 0, s[82:83]
	s_mov_b32 m0, s24
	s_nop 0
	global_load_lds_dwordx4 v[240:241], off
	s_waitcnt vmcnt(8)
	s_waitcnt lgkmcnt(0)
	s_barrier
	s_setprio 3
	v_mfma_f32_16x16x32_bf16 v[142:145], v[110:113], v[162:165], v[142:145]
	v_mfma_f32_16x16x32_bf16 v[138:141], v[122:125], v[162:165], v[138:141]
	v_mfma_f32_16x16x32_bf16 v[118:121], v[110:113], v[190:193], v[118:121]
	v_mfma_f32_16x16x32_bf16 v[106:109], v[122:125], v[190:193], v[106:109]
	v_mfma_f32_16x16x32_bf16 v[94:97], v[110:113], v[202:205], v[94:97]
	v_mfma_f32_16x16x32_bf16 v[90:93], v[122:125], v[202:205], v[90:93]
	v_mfma_f32_16x16x32_bf16 v[78:81], v[110:113], v[214:217], v[78:81]
	v_mfma_f32_16x16x32_bf16 v[74:77], v[122:125], v[214:217], v[74:77]
	v_mfma_f32_16x16x32_bf16 v[142:145], v[114:117], v[186:189], v[142:145]
	v_mfma_f32_16x16x32_bf16 v[138:141], v[130:133], v[186:189], v[138:141]
	v_mfma_f32_16x16x32_bf16 v[118:121], v[114:117], v[198:201], v[118:121]
	v_mfma_f32_16x16x32_bf16 v[106:109], v[130:133], v[198:201], v[106:109]
	v_mfma_f32_16x16x32_bf16 v[94:97], v[114:117], v[206:209], v[94:97]
	v_mfma_f32_16x16x32_bf16 v[90:93], v[130:133], v[206:209], v[90:93]
	v_mfma_f32_16x16x32_bf16 v[78:81], v[114:117], v[234:237], v[78:81]
	v_mfma_f32_16x16x32_bf16 v[74:77], v[130:133], v[234:237], v[74:77]
	v_mfma_f32_16x16x32_bf16 v[134:137], v[146:149], v[162:165], v[134:137]
	v_mfma_f32_16x16x32_bf16 v[126:129], v[154:157], v[162:165], v[126:129]
	v_mfma_f32_16x16x32_bf16 v[102:105], v[146:149], v[190:193], v[102:105]
	v_mfma_f32_16x16x32_bf16 v[98:101], v[154:157], v[190:193], v[98:101]
	v_mfma_f32_16x16x32_bf16 v[86:89], v[146:149], v[202:205], v[86:89]
	v_mfma_f32_16x16x32_bf16 v[82:85], v[154:157], v[202:205], v[82:85]
	v_mfma_f32_16x16x32_bf16 v[70:73], v[146:149], v[214:217], v[70:73]
	v_mfma_f32_16x16x32_bf16 v[66:69], v[154:157], v[214:217], v[66:69]
	v_mfma_f32_16x16x32_bf16 v[134:137], v[150:153], v[186:189], v[134:137]
	v_mfma_f32_16x16x32_bf16 v[126:129], v[158:161], v[186:189], v[126:129]
	v_mfma_f32_16x16x32_bf16 v[102:105], v[150:153], v[198:201], v[102:105]
	v_mfma_f32_16x16x32_bf16 v[98:101], v[158:161], v[198:201], v[98:101]
	v_mfma_f32_16x16x32_bf16 v[86:89], v[150:153], v[206:209], v[86:89]
	v_mfma_f32_16x16x32_bf16 v[82:85], v[158:161], v[206:209], v[82:85]
	v_mfma_f32_16x16x32_bf16 v[70:73], v[150:153], v[234:237], v[70:73]
	v_mfma_f32_16x16x32_bf16 v[66:69], v[158:161], v[234:237], v[66:69]
	s_setprio 0
	s_barrier
	s_add_i32 s20, s20, s16
	v_lshl_add_u64 v[240:241], v[218:219], 0, s[64:65]
	s_mov_b32 m0, s20
	ds_read_b128 v[162:165], v196 offset:49152
	ds_read_b128 v[186:189], v196 offset:50176
	ds_read_b128 v[190:193], v196 offset:51200
	ds_read_b128 v[198:201], v196 offset:52224
	ds_read_b128 v[202:205], v196 offset:53248
	ds_read_b128 v[206:209], v196 offset:54272
	ds_read_b128 v[214:217], v196 offset:55296
	ds_read_b128 v[234:237], v196 offset:56320
	global_load_lds_dwordx4 v[240:241], off
	v_lshl_add_u64 v[240:241], v[218:219], 0, s[62:63]
	s_add_i32 m0, s20, 0x2000
	s_add_i32 s20, s21, s16
	global_load_lds_dwordx4 v[240:241], off
	v_lshl_add_u64 v[240:241], v[218:219], 0, s[56:57]
	s_mov_b32 m0, s20
	v_lshl_add_u64 v[218:219], v[218:219], 0, s[58:59]
	global_load_lds_dwordx4 v[240:241], off
	s_add_i32 m0, s20, 0x2000
	s_nop 0
	global_load_lds_dwordx4 v[218:219], off
	v_lshl_add_u64 v[218:219], v[238:239], 0, s[66:67]
	s_mov_b32 m0, s29
	s_nop 0
	global_load_lds_dwordx4 v[218:219], off
	v_lshl_add_u64 v[218:219], v[238:239], 0, s[84:85]
	s_mov_b32 m0, s30
	s_nop 0
	global_load_lds_dwordx4 v[218:219], off
	s_waitcnt vmcnt(8)
	s_waitcnt lgkmcnt(0)
	s_barrier
	s_setprio 3
	v_mfma_f32_16x16x32_bf16 v[62:65], v[110:113], v[162:165], v[62:65]
	v_mfma_f32_16x16x32_bf16 v[58:61], v[122:125], v[162:165], v[58:61]
	v_mfma_f32_16x16x32_bf16 v[46:49], v[110:113], v[190:193], v[46:49]
	v_mfma_f32_16x16x32_bf16 v[42:45], v[122:125], v[190:193], v[42:45]
	v_mfma_f32_16x16x32_bf16 v[30:33], v[110:113], v[202:205], v[30:33]
	v_mfma_f32_16x16x32_bf16 v[26:29], v[122:125], v[202:205], v[26:29]
	v_mfma_f32_16x16x32_bf16 v[14:17], v[110:113], v[214:217], v[14:17]
	v_mfma_f32_16x16x32_bf16 v[10:13], v[122:125], v[214:217], v[10:13]
	v_mfma_f32_16x16x32_bf16 v[62:65], v[114:117], v[186:189], v[62:65]
	v_mfma_f32_16x16x32_bf16 v[58:61], v[130:133], v[186:189], v[58:61]
	v_mfma_f32_16x16x32_bf16 v[46:49], v[114:117], v[198:201], v[46:49]
	v_mfma_f32_16x16x32_bf16 v[42:45], v[130:133], v[198:201], v[42:45]
	v_mfma_f32_16x16x32_bf16 v[30:33], v[114:117], v[206:209], v[30:33]
	v_mfma_f32_16x16x32_bf16 v[26:29], v[130:133], v[206:209], v[26:29]
	v_mfma_f32_16x16x32_bf16 v[14:17], v[114:117], v[234:237], v[14:17]
	v_mfma_f32_16x16x32_bf16 v[10:13], v[130:133], v[234:237], v[10:13]
	v_mfma_f32_16x16x32_bf16 v[54:57], v[146:149], v[162:165], v[54:57]
	v_mfma_f32_16x16x32_bf16 v[50:53], v[154:157], v[162:165], v[50:53]
	v_mfma_f32_16x16x32_bf16 v[38:41], v[146:149], v[190:193], v[38:41]
	v_mfma_f32_16x16x32_bf16 v[34:37], v[154:157], v[190:193], v[34:37]
	v_mfma_f32_16x16x32_bf16 v[22:25], v[146:149], v[202:205], v[22:25]
	v_mfma_f32_16x16x32_bf16 v[18:21], v[154:157], v[202:205], v[18:21]
	v_mfma_f32_16x16x32_bf16 v[6:9], v[146:149], v[214:217], v[6:9]
	v_mfma_f32_16x16x32_bf16 v[2:5], v[154:157], v[214:217], v[2:5]
	v_mfma_f32_16x16x32_bf16 v[54:57], v[150:153], v[186:189], v[54:57]
	v_mfma_f32_16x16x32_bf16 v[50:53], v[158:161], v[186:189], v[50:53]
	v_mfma_f32_16x16x32_bf16 v[38:41], v[150:153], v[198:201], v[38:41]
	v_mfma_f32_16x16x32_bf16 v[34:37], v[158:161], v[198:201], v[34:37]
	v_mfma_f32_16x16x32_bf16 v[22:25], v[150:153], v[206:209], v[22:25]
	v_mfma_f32_16x16x32_bf16 v[18:21], v[158:161], v[206:209], v[18:21]
	v_mfma_f32_16x16x32_bf16 v[6:9], v[150:153], v[234:237], v[6:9]
	v_mfma_f32_16x16x32_bf16 v[2:5], v[158:161], v[234:237], v[2:5]
	s_setprio 0
	s_barrier
	s_add_i32 s37, s37, 2
	s_add_u32 s19, s19, 0x10000
	s_addc_u32 s36, s36, 0
	s_add_u32 s14, s14, 0x100
	s_addc_u32 s15, s15, 0
	s_cmp_gt_u32 s37, 41
	s_cbranch_scc0 .LBB0_1455
	s_and_b64 vcc, exec, s[10:11]
	s_cbranch_vccz .LBB0_1458
	s_barrier
